# forget-logit tile mainloop: LDS-DMA into a 3-stage swizzled ring (K step 64), two K steps in flight, one barrier per step
# speedup vs baseline: 1.0039x; 1.0039x over previous
.LBB0_233:
	s_cmp_eq_u32 s52, 2
	s_cbranch_scc0 .LBB0_257
	v_readfirstlane_b32 s98, v204
	s_lshr_b32 s98, s98, 7
	s_ashr_i32 s77, s76, 31
	s_lshl_b64 s[4:5], s[76:77], 18
	s_add_u32 s0, s10, s4
	s_addc_u32 s1, s11, s5
	s_ashr_i32 s75, s74, 31
	s_lshl_b64 s[4:5], s[74:75], 18
	s_add_u32 s4, s12, s4
	s_addc_u32 s5, s13, s5
	v_lshrrev_b32_e32 v32, 3, v204
	v_lshrrev_b32_e32 v33, 4, v204
	v_xor_b32_e32 v33, v33, v204
	v_and_b32_e32 v33, 7, v33
	v_lshlrev_b32_e32 v33, 4, v33
	v_lshl_or_b32 v32, v32, 11, v33
	v_add_u32_e32 v33, 0x10000, v32
	v_add_u32_e32 v34, 0x20000, v32
	v_add_u32_e32 v35, 0x30000, v32
	v_and_b32_e32 v36, 31, v204
	v_bfe_u32 v37, v204, 5, 1
	v_bfe_u32 v38, v36, 1, 3
	v_xor_b32_e32 v37, v37, v38
	v_lshlrev_b32_e32 v37, 4, v37
	v_lshl_or_b32 v37, v36, 7, v37
	v_bfe_u32 v38, v204, 6, 1
	v_lshl_or_b32 v38, v38, 13, v37
	v_add_u32_e32 v39, 0x4000, v37
	v_lshrrev_b32_e32 v40, 6, v204
	v_lshlrev_b32_e32 v40, 10, v40
	s_nop 1
	v_readfirstlane_b32 vcc_lo, v40
	s_mov_b32 s34, 0
	s_mov_b32 s6, 0
	s_mov_b32 m0, vcc_lo
	s_nop 0
	global_load_lds_dwordx4 v32, s[0:1]
	s_add_u32 m0, m0, 0x1000
	s_nop 0
	global_load_lds_dwordx4 v33, s[0:1]
	s_add_u32 m0, m0, 0x1000
	s_nop 0
	global_load_lds_dwordx4 v34, s[0:1]
	s_add_u32 m0, m0, 0x1000
	s_nop 0
	global_load_lds_dwordx4 v35, s[0:1]
	s_add_u32 m0, m0, 0x1000
	s_nop 0
	global_load_lds_dwordx4 v32, s[4:5]
	s_add_u32 s0, s0, 0x80
	s_addc_u32 s1, s1, 0
	s_add_u32 s4, s4, 0x80
	s_addc_u32 s5, s5, 0
	s_add_u32 m0, vcc_lo, 0x5000
	s_nop 0
	global_load_lds_dwordx4 v32, s[0:1]
	s_add_u32 m0, m0, 0x1000
	s_nop 0
	global_load_lds_dwordx4 v33, s[0:1]
	s_add_u32 m0, m0, 0x1000
	s_nop 0
	global_load_lds_dwordx4 v34, s[0:1]
	s_add_u32 m0, m0, 0x1000
	s_nop 0
	global_load_lds_dwordx4 v35, s[0:1]
	s_add_u32 m0, m0, 0x1000
	s_nop 0
	global_load_lds_dwordx4 v32, s[4:5]
	s_add_u32 s0, s0, 0x80
	s_addc_u32 s1, s1, 0
	s_add_u32 s4, s4, 0x80
	s_addc_u32 s5, s5, 0
	v_mov_b32_e32 v0, 0
	v_mov_b32_e32 v1, 0
	v_mov_b32_e32 v2, 0
	v_mov_b32_e32 v3, 0
	v_mov_b32_e32 v4, 0
	v_mov_b32_e32 v5, 0
	v_mov_b32_e32 v6, 0
	v_mov_b32_e32 v7, 0
	v_mov_b32_e32 v8, 0
	v_mov_b32_e32 v9, 0
	v_mov_b32_e32 v10, 0
	v_mov_b32_e32 v11, 0
	v_mov_b32_e32 v12, 0
	v_mov_b32_e32 v13, 0
	v_mov_b32_e32 v14, 0
	v_mov_b32_e32 v15, 0
	v_mov_b32_e32 v16, 0
	v_mov_b32_e32 v17, 0
	v_mov_b32_e32 v18, 0
	v_mov_b32_e32 v19, 0
	v_mov_b32_e32 v20, 0
	v_mov_b32_e32 v21, 0
	v_mov_b32_e32 v22, 0
	v_mov_b32_e32 v23, 0
	v_mov_b32_e32 v24, 0
	v_mov_b32_e32 v25, 0
	v_mov_b32_e32 v26, 0
	v_mov_b32_e32 v27, 0
	v_mov_b32_e32 v28, 0
	v_mov_b32_e32 v29, 0
	v_mov_b32_e32 v30, 0
	v_mov_b32_e32 v31, 0
.Lp2n_top:
	s_cmp_eq_u32 s34, 15
	s_cbranch_scc1 .Lp2n_w0
	s_waitcnt vmcnt(5)
	s_branch .Lp2n_bar

.Lp2n_bar:
	s_barrier
	s_cmp_gt_u32 s34, 13
	s_cbranch_scc1 .Lp2n_comp
	s_add_u32 vcc_hi, s6, 0xa000
	s_sub_u32 m0, vcc_hi, 0xf000
	s_cmp_lt_u32 s6, 0x5000
	s_cselect_b32 vcc_hi, vcc_hi, m0
	s_add_u32 m0, vcc_hi, vcc_lo
	s_nop 0
	global_load_lds_dwordx4 v32, s[0:1]
	s_add_u32 m0, m0, 0x1000
	s_nop 0
	global_load_lds_dwordx4 v33, s[0:1]
	s_add_u32 m0, m0, 0x1000
	s_nop 0
	global_load_lds_dwordx4 v34, s[0:1]
	s_add_u32 m0, m0, 0x1000
	s_nop 0
	global_load_lds_dwordx4 v35, s[0:1]
	s_add_u32 m0, m0, 0x1000
	s_nop 0
	global_load_lds_dwordx4 v32, s[4:5]
	s_add_u32 s0, s0, 0x80
	s_addc_u32 s1, s1, 0
	s_add_u32 s4, s4, 0x80
	s_addc_u32 s5, s5, 0
.Lp2n_comp:
	s_cmp_eq_u32 s98, 1
	s_cbranch_scc1 .Lp2n_skip
	v_add_u32_e32 v41, s6, v38
	v_xor_b32_e32 v42, 32, v41
	v_add_u32_e32 v43, s6, v39
	v_xor_b32_e32 v44, 32, v43
	ds_read_b128 v[68:71], v41
	ds_read_b128 v[72:75], v43
	ds_read_b128 v[76:79], v42
	ds_read_b128 v[80:83], v44
	s_waitcnt lgkmcnt(2)
	v_mfma_f32_32x32x16_bf16 v[16:31], v[68:71], v[72:75], v[16:31]
	ds_read_b128 v[68:71], v41 offset:4096
	ds_read_b128 v[84:87], v42 offset:4096
	s_waitcnt lgkmcnt(1)
	v_mfma_f32_32x32x16_bf16 v[0:15], v[68:71], v[72:75], v[0:15]
	v_mfma_f32_32x32x16_bf16 v[16:31], v[76:79], v[80:83], v[16:31]
	s_waitcnt lgkmcnt(0)
	v_mfma_f32_32x32x16_bf16 v[0:15], v[84:87], v[80:83], v[0:15]
	v_xor_b32_e32 v41, 64, v41
	v_xor_b32_e32 v42, 64, v42
	v_xor_b32_e32 v43, 64, v43
	v_xor_b32_e32 v44, 64, v44
	ds_read_b128 v[68:71], v41
	ds_read_b128 v[72:75], v43
	ds_read_b128 v[76:79], v42
	ds_read_b128 v[80:83], v44
	s_waitcnt lgkmcnt(2)
	v_mfma_f32_32x32x16_bf16 v[16:31], v[68:71], v[72:75], v[16:31]
	ds_read_b128 v[68:71], v41 offset:4096
	ds_read_b128 v[84:87], v42 offset:4096
	s_waitcnt lgkmcnt(1)
	v_mfma_f32_32x32x16_bf16 v[0:15], v[68:71], v[72:75], v[0:15]
	v_mfma_f32_32x32x16_bf16 v[16:31], v[76:79], v[80:83], v[16:31]
	s_waitcnt lgkmcnt(0)
	v_mfma_f32_32x32x16_bf16 v[0:15], v[84:87], v[80:83], v[0:15]
.Lp2n_skip:
	s_add_u32 s6, s6, 0x5000
	s_cmp_eq_u32 s6, 0xf000
	s_cselect_b32 s6, 0, s6
	s_add_i32 s34, s34, 1
	s_cmp_lg_u32 s34, 16
	s_cbranch_scc1 .Lp2n_top
	s_barrier
